# prompt cross-attention unit: K/V tile loads of each stage issued together, next K half prefetched during QK
# speedup vs baseline: 1.0230x; 1.0039x over previous
.LBB0_179:
	s_andn2_b64 vcc, exec, s[6:7]
	s_cbranch_vccnz .LBB0_150
	s_andn2_b64 vcc, exec, s[18:19]
	s_cbranch_vccnz .LBB0_150
	s_ashr_i32 s0, s24, 7
	s_lshl_b32 s7, s24, 4
	s_lshl_b32 s6, s0, 11
	s_and_b32 s7, s7, 0x780
	s_or_b32 s6, s6, s7
	v_add_u32_e32 v0, s6, v176
	s_lshl_b32 s6, s0, 8
	s_ashr_i32 s7, s6, 31
	s_mov_b64 s[20:21], s[94:95]
	s_lshl_b64 s[6:7], s[6:7], 12
	s_add_u32 s0, s20, s53
	s_addc_u32 s22, s21, 0
	s_add_u32 s6, s0, s6
	s_addc_u32 s7, s22, s7
	s_lshl_b32 s0, s24, 8
	s_and_b32 s0, s0, 0x600
	v_ashrrev_i32_e32 v1, 31, v0
	s_add_u32 s6, s6, s0
	v_lshlrev_b64 v[0:1], 11, v[0:1]
	s_addc_u32 s7, s7, 0
	v_lshl_add_u64 v[0:1], s[20:21], 0, v[0:1]
	s_add_u32 s6, s6, 0x5100000
	v_lshlrev_b32_e32 v152, 1, v96
	v_lshl_add_u64 v[52:53], v[0:1], 0, s[0:1]
	s_addc_u32 s7, s7, 0
	v_lshl_add_u64 v[0:1], v[52:53], 0, v[152:153]
	s_mov_b64 s[20:21], 0x1b500000
	s_mov_b32 s0, 0x1b500000
	v_lshl_add_u64 v[2:3], v[0:1], 0, s[20:21]
	v_add_co_u32_e32 v0, vcc, s0, v0
	v_lshl_add_u64 v[32:33], s[6:7], 0, v[100:101]
	s_nop 0
	v_addc_co_u32_e32 v1, vcc, 0, v1, vcc
	v_lshl_add_u64 v[32:33], v[102:103], 1, v[32:33]
	flat_load_dwordx4 v[28:31], v[0:1]
	flat_load_dwordx4 v[24:27], v[2:3] offset:64
	flat_load_dwordx4 v[20:23], v[2:3] offset:128
	flat_load_dwordx4 v[16:19], v[2:3] offset:192
	flat_load_dwordx4 v[12:15], v[2:3] offset:256
	flat_load_dwordx4 v[8:11], v[2:3] offset:320
	flat_load_dwordx4 v[4:7], v[2:3] offset:384
	s_nop 0
	flat_load_dwordx4 v[0:3], v[2:3] offset:448
	s_nop 0
	v_lshl_add_u64 v[34:35], s[6:7], 0, v[104:105]
	v_lshl_add_u64 v[34:35], v[106:107], 1, v[34:35]
	v_lshl_add_u64 v[36:37], s[6:7], 0, v[108:109]
	v_lshl_add_u64 v[36:37], v[110:111], 1, v[36:37]
	v_lshl_add_u64 v[38:39], s[6:7], 0, v[112:113]
	v_lshl_add_u64 v[38:39], v[114:115], 1, v[38:39]
	v_lshl_add_u64 v[40:41], s[6:7], 0, v[116:117]
	v_lshl_add_u64 v[40:41], v[118:119], 1, v[40:41]
	v_lshl_add_u64 v[42:43], s[6:7], 0, v[120:121]
	v_lshl_add_u64 v[42:43], v[122:123], 1, v[42:43]
	v_lshl_add_u64 v[44:45], s[6:7], 0, v[124:125]
	v_lshl_add_u64 v[44:45], v[126:127], 1, v[44:45]
	v_lshl_add_u64 v[46:47], s[6:7], 0, v[128:129]
	v_lshl_add_u64 v[46:47], v[130:131], 1, v[46:47]
	global_load_dwordx4 v[224:227], v[32:33], off
	global_load_dwordx4 v[228:231], v[34:35], off
	global_load_dwordx4 v[232:235], v[36:37], off
	global_load_dwordx4 v[236:239], v[38:39], off
	global_load_dwordx4 v[240:243], v[40:41], off
	global_load_dwordx4 v[244:247], v[42:43], off
	global_load_dwordx4 v[248:251], v[44:45], off
	global_load_dwordx4 v[48:51], v[46:47], off
	s_waitcnt vmcnt(0) lgkmcnt(0)
	ds_write_b128 v195, v[224:227]
	ds_write_b128 v196, v[228:231]
	ds_write_b128 v197, v[232:235]
	ds_write_b128 v198, v[236:239]
	ds_write_b128 v199, v[240:243]
	ds_write_b128 v200, v[244:247]
	ds_write_b128 v201, v[248:251]
	ds_write_b128 v202, v[48:51]
	s_waitcnt lgkmcnt(0)
	global_load_dwordx4 v[224:227], v[32:33], off offset:256
	global_load_dwordx4 v[228:231], v[34:35], off offset:256
	global_load_dwordx4 v[232:235], v[36:37], off offset:256
	global_load_dwordx4 v[236:239], v[38:39], off offset:256
	global_load_dwordx4 v[240:243], v[40:41], off offset:256
	global_load_dwordx4 v[244:247], v[42:43], off offset:256
	global_load_dwordx4 v[248:251], v[44:45], off offset:256
	s_barrier
	ds_read_b128 v[48:51], v203
	ds_read_b128 v[54:57], v203 offset:4352
	ds_read_b128 v[58:61], v203 offset:8704
	ds_read_b128 v[62:65], v204
	s_waitcnt lgkmcnt(3)
	v_mfma_f32_16x16x32_bf16 v[48:51], v[48:51], v[28:31], 0
	s_waitcnt lgkmcnt(2)
	v_mfma_f32_16x16x32_bf16 v[54:57], v[54:57], v[28:31], 0
	s_waitcnt lgkmcnt(1)
	v_mfma_f32_16x16x32_bf16 v[58:61], v[58:61], v[28:31], 0
	s_waitcnt lgkmcnt(0)
	v_mfma_f32_16x16x32_bf16 v[62:65], v[62:65], v[28:31], 0
	ds_read_b128 v[66:69], v203 offset:17408
	ds_read_b128 v[70:73], v203 offset:21760
	ds_read_b128 v[74:77], v203 offset:26112
	ds_read_b128 v[78:81], v205
	s_waitcnt lgkmcnt(3)
	v_mfma_f32_16x16x32_bf16 v[66:69], v[66:69], v[28:31], 0
	s_waitcnt lgkmcnt(2)
	v_mfma_f32_16x16x32_bf16 v[70:73], v[70:73], v[28:31], 0
	s_waitcnt lgkmcnt(1)
	v_mfma_f32_16x16x32_bf16 v[74:77], v[74:77], v[28:31], 0
	s_waitcnt lgkmcnt(0)
	v_mfma_f32_16x16x32_bf16 v[78:81], v[78:81], v[28:31], 0
	ds_read_b128 v[82:85], v203 offset:34816
	ds_read_b128 v[86:89], v203 offset:39168
	ds_read_b128 v[90:93], v203 offset:43520
	ds_read_b128 v[162:165], v206
	s_waitcnt lgkmcnt(3)
	v_mfma_f32_16x16x32_bf16 v[82:85], v[82:85], v[28:31], 0
	s_waitcnt lgkmcnt(2)
	v_mfma_f32_16x16x32_bf16 v[86:89], v[86:89], v[28:31], 0
	s_waitcnt lgkmcnt(1)
	v_mfma_f32_16x16x32_bf16 v[90:93], v[90:93], v[28:31], 0
	s_waitcnt lgkmcnt(0)
	v_mfma_f32_16x16x32_bf16 v[162:165], v[162:165], v[28:31], 0
	ds_read_b128 v[166:169], v203 offset:52224
	ds_read_b128 v[170:173], v203 offset:56576
	ds_read_b128 v[216:219], v203 offset:60928
	ds_read_b128 v[220:223], v207
	s_waitcnt lgkmcnt(3)
	v_mfma_f32_16x16x32_bf16 v[166:169], v[166:169], v[28:31], 0
	s_waitcnt lgkmcnt(2)
	v_mfma_f32_16x16x32_bf16 v[170:173], v[170:173], v[28:31], 0
	s_waitcnt lgkmcnt(1)
	v_mfma_f32_16x16x32_bf16 v[216:219], v[216:219], v[28:31], 0
	s_waitcnt lgkmcnt(0)
	v_mfma_f32_16x16x32_bf16 v[28:31], v[220:223], v[28:31], 0
	ds_read_b128 v[220:223], v203 offset:64
	s_waitcnt lgkmcnt(0)
	v_mfma_f32_16x16x32_bf16 v[48:51], v[220:223], v[24:27], v[48:51]
	ds_read_b128 v[220:223], v203 offset:4416
	s_waitcnt lgkmcnt(0)
	v_mfma_f32_16x16x32_bf16 v[54:57], v[220:223], v[24:27], v[54:57]
	ds_read_b128 v[220:223], v203 offset:8768
	s_waitcnt lgkmcnt(0)
	v_mfma_f32_16x16x32_bf16 v[58:61], v[220:223], v[24:27], v[58:61]
	ds_read_b128 v[220:223], v204 offset:64
	s_waitcnt lgkmcnt(0)
	v_mfma_f32_16x16x32_bf16 v[62:65], v[220:223], v[24:27], v[62:65]
	ds_read_b128 v[220:223], v203 offset:17472
	s_waitcnt lgkmcnt(0)
	v_mfma_f32_16x16x32_bf16 v[66:69], v[220:223], v[24:27], v[66:69]
	ds_read_b128 v[220:223], v203 offset:21824
	s_waitcnt lgkmcnt(0)
	v_mfma_f32_16x16x32_bf16 v[70:73], v[220:223], v[24:27], v[70:73]
	ds_read_b128 v[220:223], v203 offset:26176
	s_waitcnt lgkmcnt(0)
	v_mfma_f32_16x16x32_bf16 v[74:77], v[220:223], v[24:27], v[74:77]
	ds_read_b128 v[220:223], v205 offset:64
	s_waitcnt lgkmcnt(0)
	v_mfma_f32_16x16x32_bf16 v[78:81], v[220:223], v[24:27], v[78:81]
	ds_read_b128 v[220:223], v203 offset:34880
	s_waitcnt lgkmcnt(0)
	v_mfma_f32_16x16x32_bf16 v[82:85], v[220:223], v[24:27], v[82:85]
	ds_read_b128 v[220:223], v203 offset:39232
	s_waitcnt lgkmcnt(0)
	v_mfma_f32_16x16x32_bf16 v[86:89], v[220:223], v[24:27], v[86:89]
	ds_read_b128 v[220:223], v203 offset:43584
	s_waitcnt lgkmcnt(0)
	v_mfma_f32_16x16x32_bf16 v[90:93], v[220:223], v[24:27], v[90:93]
	ds_read_b128 v[220:223], v206 offset:64
	s_waitcnt lgkmcnt(0)
	v_mfma_f32_16x16x32_bf16 v[162:165], v[220:223], v[24:27], v[162:165]
	ds_read_b128 v[220:223], v203 offset:52288
	s_waitcnt lgkmcnt(0)
	v_mfma_f32_16x16x32_bf16 v[166:169], v[220:223], v[24:27], v[166:169]
	ds_read_b128 v[220:223], v203 offset:56640
	s_waitcnt lgkmcnt(0)
	v_mfma_f32_16x16x32_bf16 v[170:173], v[220:223], v[24:27], v[170:173]
	ds_read_b128 v[220:223], v203 offset:60992
	s_waitcnt lgkmcnt(0)
	v_mfma_f32_16x16x32_bf16 v[216:219], v[220:223], v[24:27], v[216:219]
	ds_read_b128 v[220:223], v207 offset:64
	s_waitcnt lgkmcnt(0)
	v_mfma_f32_16x16x32_bf16 v[24:27], v[220:223], v[24:27], v[28:31]
	s_nop 2
	ds_read_b128 v[28:31], v203 offset:128
	s_waitcnt lgkmcnt(0)
	v_mfma_f32_16x16x32_bf16 v[28:31], v[28:31], v[20:23], v[48:51]
	s_nop 2
	ds_read_b128 v[48:51], v203 offset:4480
	s_waitcnt lgkmcnt(0)
	v_mfma_f32_16x16x32_bf16 v[48:51], v[48:51], v[20:23], v[54:57]
	s_nop 2
	ds_read_b128 v[54:57], v203 offset:8832
	s_waitcnt lgkmcnt(0)
	v_mfma_f32_16x16x32_bf16 v[54:57], v[54:57], v[20:23], v[58:61]
	s_nop 2
	ds_read_b128 v[58:61], v204 offset:128
	s_waitcnt lgkmcnt(0)
	v_mfma_f32_16x16x32_bf16 v[58:61], v[58:61], v[20:23], v[62:65]
	s_nop 2
	ds_read_b128 v[62:65], v203 offset:17536
	s_waitcnt lgkmcnt(0)
	v_mfma_f32_16x16x32_bf16 v[62:65], v[62:65], v[20:23], v[66:69]
	s_nop 2
	ds_read_b128 v[66:69], v203 offset:21888
	s_waitcnt lgkmcnt(0)
	v_mfma_f32_16x16x32_bf16 v[66:69], v[66:69], v[20:23], v[70:73]
	s_nop 2
	ds_read_b128 v[70:73], v203 offset:26240
	s_waitcnt lgkmcnt(0)
	v_mfma_f32_16x16x32_bf16 v[70:73], v[70:73], v[20:23], v[74:77]
	s_nop 2
	ds_read_b128 v[74:77], v205 offset:128
	s_waitcnt lgkmcnt(0)
	v_mfma_f32_16x16x32_bf16 v[74:77], v[74:77], v[20:23], v[78:81]
	s_nop 2
	ds_read_b128 v[78:81], v203 offset:34944
	s_waitcnt lgkmcnt(0)
	v_mfma_f32_16x16x32_bf16 v[78:81], v[78:81], v[20:23], v[82:85]
	s_nop 2
	ds_read_b128 v[82:85], v203 offset:39296
	s_waitcnt lgkmcnt(0)
	v_mfma_f32_16x16x32_bf16 v[82:85], v[82:85], v[20:23], v[86:89]
	s_nop 2
	ds_read_b128 v[86:89], v203 offset:43648
	s_waitcnt lgkmcnt(0)
	v_mfma_f32_16x16x32_bf16 v[86:89], v[86:89], v[20:23], v[90:93]
	s_nop 2
	ds_read_b128 v[90:93], v206 offset:128
	s_waitcnt lgkmcnt(0)
	v_mfma_f32_16x16x32_bf16 v[90:93], v[90:93], v[20:23], v[162:165]
	s_nop 2
	ds_read_b128 v[162:165], v203 offset:52352
	s_waitcnt lgkmcnt(0)
	v_mfma_f32_16x16x32_bf16 v[162:165], v[162:165], v[20:23], v[166:169]
	s_nop 2
	ds_read_b128 v[166:169], v203 offset:56704
	s_waitcnt lgkmcnt(0)
	v_mfma_f32_16x16x32_bf16 v[166:169], v[166:169], v[20:23], v[170:173]
	s_nop 2
	ds_read_b128 v[170:173], v203 offset:61056
	s_waitcnt lgkmcnt(0)
	v_mfma_f32_16x16x32_bf16 v[170:173], v[170:173], v[20:23], v[216:219]
	s_nop 2
	ds_read_b128 v[216:219], v207 offset:128
	s_waitcnt lgkmcnt(0)
	v_mfma_f32_16x16x32_bf16 v[20:23], v[216:219], v[20:23], v[24:27]
	s_nop 2
	ds_read_b128 v[24:27], v203 offset:192
	s_waitcnt lgkmcnt(0)
	v_mfma_f32_16x16x32_bf16 v[24:27], v[24:27], v[16:19], v[28:31]
	s_nop 2
	ds_read_b128 v[28:31], v203 offset:4544
	s_waitcnt lgkmcnt(0)
	v_mfma_f32_16x16x32_bf16 v[28:31], v[28:31], v[16:19], v[48:51]
	s_nop 2
	ds_read_b128 v[48:51], v203 offset:8896
	s_waitcnt lgkmcnt(0)
	v_mfma_f32_16x16x32_bf16 v[48:51], v[48:51], v[16:19], v[54:57]
	s_nop 2
	ds_read_b128 v[54:57], v204 offset:192
	s_waitcnt lgkmcnt(0)
	v_mfma_f32_16x16x32_bf16 v[54:57], v[54:57], v[16:19], v[58:61]
	s_nop 2
	ds_read_b128 v[58:61], v203 offset:17600
	s_waitcnt lgkmcnt(0)
	v_mfma_f32_16x16x32_bf16 v[58:61], v[58:61], v[16:19], v[62:65]
	s_nop 2
	ds_read_b128 v[62:65], v203 offset:21952
	s_waitcnt lgkmcnt(0)
	v_mfma_f32_16x16x32_bf16 v[62:65], v[62:65], v[16:19], v[66:69]
	s_nop 2
	ds_read_b128 v[66:69], v203 offset:26304
	s_waitcnt lgkmcnt(0)
	v_mfma_f32_16x16x32_bf16 v[66:69], v[66:69], v[16:19], v[70:73]
	s_nop 2
	ds_read_b128 v[70:73], v205 offset:192
	s_waitcnt lgkmcnt(0)
	v_mfma_f32_16x16x32_bf16 v[70:73], v[70:73], v[16:19], v[74:77]
	s_nop 2
	ds_read_b128 v[74:77], v203 offset:35008
	s_waitcnt lgkmcnt(0)
	v_mfma_f32_16x16x32_bf16 v[74:77], v[74:77], v[16:19], v[78:81]
	s_nop 2
	ds_read_b128 v[78:81], v203 offset:39360
	s_waitcnt lgkmcnt(0)
	v_mfma_f32_16x16x32_bf16 v[78:81], v[78:81], v[16:19], v[82:85]
	s_nop 2
	ds_read_b128 v[82:85], v203 offset:43712
	s_waitcnt lgkmcnt(0)
	v_mfma_f32_16x16x32_bf16 v[82:85], v[82:85], v[16:19], v[86:89]
	s_nop 2
	ds_read_b128 v[86:89], v206 offset:192
	s_waitcnt lgkmcnt(0)
	v_mfma_f32_16x16x32_bf16 v[86:89], v[86:89], v[16:19], v[90:93]
	s_nop 2
	ds_read_b128 v[90:93], v203 offset:52416
	s_waitcnt lgkmcnt(0)
	v_mfma_f32_16x16x32_bf16 v[90:93], v[90:93], v[16:19], v[162:165]
	s_nop 2
	ds_read_b128 v[162:165], v203 offset:56768
	s_waitcnt lgkmcnt(0)
	v_mfma_f32_16x16x32_bf16 v[162:165], v[162:165], v[16:19], v[166:169]
	s_nop 2
	ds_read_b128 v[166:169], v203 offset:61120
	s_waitcnt lgkmcnt(0)
	v_mfma_f32_16x16x32_bf16 v[166:169], v[166:169], v[16:19], v[170:173]
	s_nop 2
	ds_read_b128 v[170:173], v207 offset:192
	s_waitcnt lgkmcnt(0)
	v_mfma_f32_16x16x32_bf16 v[16:19], v[170:173], v[16:19], v[20:23]
	s_barrier
	s_nop 1
	global_load_dwordx4 v[20:23], v[46:47], off offset:256
	s_waitcnt vmcnt(0) lgkmcnt(0)
	ds_write_b128 v195, v[224:227]
	ds_write_b128 v196, v[228:231]
	ds_write_b128 v197, v[232:235]
	ds_write_b128 v198, v[236:239]
	ds_write_b128 v199, v[240:243]
	ds_write_b128 v200, v[244:247]
	ds_write_b128 v201, v[248:251]
	ds_write_b128 v202, v[20:23]
	s_waitcnt lgkmcnt(0)
	s_barrier
	ds_read_b128 v[20:23], v203
	ds_read_b128 v[32:35], v203 offset:4352
	s_waitcnt lgkmcnt(1)
	v_mfma_f32_16x16x32_bf16 v[20:23], v[20:23], v[12:15], v[24:27]
	s_nop 2
	ds_read_b128 v[24:27], v203 offset:8704
	s_waitcnt lgkmcnt(1)
	v_mfma_f32_16x16x32_bf16 v[28:31], v[32:35], v[12:15], v[28:31]
	ds_read_b128 v[32:35], v204
	s_waitcnt lgkmcnt(0)
	v_mfma_f32_16x16x32_bf16 v[32:35], v[32:35], v[12:15], v[54:57]
	v_mfma_f32_16x16x32_bf16 v[24:27], v[24:27], v[12:15], v[48:51]
	ds_read_b128 v[36:39], v203 offset:17408
	ds_read_b128 v[40:43], v203 offset:21760
	ds_read_b128 v[44:47], v203 offset:26112
	ds_read_b128 v[48:51], v205
	s_waitcnt lgkmcnt(3)
	v_mfma_f32_16x16x32_bf16 v[36:39], v[36:39], v[12:15], v[58:61]
	s_waitcnt lgkmcnt(2)
	v_mfma_f32_16x16x32_bf16 v[40:43], v[40:43], v[12:15], v[62:65]
	s_waitcnt lgkmcnt(1)
	v_mfma_f32_16x16x32_bf16 v[44:47], v[44:47], v[12:15], v[66:69]
	s_waitcnt lgkmcnt(0)
	v_mfma_f32_16x16x32_bf16 v[48:51], v[48:51], v[12:15], v[70:73]
	ds_read_b128 v[54:57], v203 offset:34816
	ds_read_b128 v[58:61], v203 offset:39168
	ds_read_b128 v[62:65], v203 offset:43520
	ds_read_b128 v[66:69], v206
	s_waitcnt lgkmcnt(3)
	v_mfma_f32_16x16x32_bf16 v[54:57], v[54:57], v[12:15], v[74:77]
	s_waitcnt lgkmcnt(2)
	v_mfma_f32_16x16x32_bf16 v[58:61], v[58:61], v[12:15], v[78:81]
	s_waitcnt lgkmcnt(1)
	v_mfma_f32_16x16x32_bf16 v[62:65], v[62:65], v[12:15], v[82:85]
	s_waitcnt lgkmcnt(0)
	v_mfma_f32_16x16x32_bf16 v[66:69], v[66:69], v[12:15], v[86:89]
	ds_read_b128 v[70:73], v203 offset:52224
	ds_read_b128 v[74:77], v203 offset:56576
	ds_read_b128 v[78:81], v203 offset:60928
	ds_read_b128 v[82:85], v207
	s_waitcnt lgkmcnt(3)
	v_mfma_f32_16x16x32_bf16 v[70:73], v[70:73], v[12:15], v[90:93]
	s_waitcnt lgkmcnt(2)
	v_mfma_f32_16x16x32_bf16 v[74:77], v[74:77], v[12:15], v[162:165]
	s_waitcnt lgkmcnt(1)
	v_mfma_f32_16x16x32_bf16 v[78:81], v[78:81], v[12:15], v[166:169]
	s_waitcnt lgkmcnt(0)
	v_mfma_f32_16x16x32_bf16 v[12:15], v[82:85], v[12:15], v[16:19]
	s_nop 2
	ds_read_b128 v[16:19], v203 offset:64
	s_waitcnt lgkmcnt(0)
	v_mfma_f32_16x16x32_bf16 v[16:19], v[16:19], v[8:11], v[20:23]
	s_nop 2
	ds_read_b128 v[20:23], v203 offset:4416
	s_waitcnt lgkmcnt(0)
	v_mfma_f32_16x16x32_bf16 v[20:23], v[20:23], v[8:11], v[28:31]
	s_nop 2
	ds_read_b128 v[28:31], v203 offset:8768
	s_waitcnt lgkmcnt(0)
	v_mfma_f32_16x16x32_bf16 v[24:27], v[28:31], v[8:11], v[24:27]
	ds_read_b128 v[28:31], v204 offset:64
	s_waitcnt lgkmcnt(0)
	v_mfma_f32_16x16x32_bf16 v[28:31], v[28:31], v[8:11], v[32:35]
	s_nop 2
	ds_read_b128 v[32:35], v203 offset:17472
	s_waitcnt lgkmcnt(0)
	v_mfma_f32_16x16x32_bf16 v[32:35], v[32:35], v[8:11], v[36:39]
	s_nop 2
	ds_read_b128 v[36:39], v203 offset:21824
	s_waitcnt lgkmcnt(0)
	v_mfma_f32_16x16x32_bf16 v[36:39], v[36:39], v[8:11], v[40:43]
	s_nop 2
	ds_read_b128 v[40:43], v203 offset:26176
	s_waitcnt lgkmcnt(0)
	v_mfma_f32_16x16x32_bf16 v[40:43], v[40:43], v[8:11], v[44:47]
	s_nop 2
	ds_read_b128 v[44:47], v205 offset:64
	s_waitcnt lgkmcnt(0)
	v_mfma_f32_16x16x32_bf16 v[44:47], v[44:47], v[8:11], v[48:51]
	s_nop 2
	ds_read_b128 v[48:51], v203 offset:34880
	s_waitcnt lgkmcnt(0)
	v_mfma_f32_16x16x32_bf16 v[48:51], v[48:51], v[8:11], v[54:57]
	s_nop 2
	ds_read_b128 v[54:57], v203 offset:39232
	s_waitcnt lgkmcnt(0)
	v_mfma_f32_16x16x32_bf16 v[54:57], v[54:57], v[8:11], v[58:61]
	s_nop 2
	ds_read_b128 v[58:61], v203 offset:43584
	s_waitcnt lgkmcnt(0)
	v_mfma_f32_16x16x32_bf16 v[58:61], v[58:61], v[8:11], v[62:65]
	s_nop 2
	ds_read_b128 v[62:65], v206 offset:64
	s_waitcnt lgkmcnt(0)
	v_mfma_f32_16x16x32_bf16 v[62:65], v[62:65], v[8:11], v[66:69]
	s_nop 2
	ds_read_b128 v[66:69], v203 offset:52288
	s_waitcnt lgkmcnt(0)
	v_mfma_f32_16x16x32_bf16 v[66:69], v[66:69], v[8:11], v[70:73]
	s_nop 2
	ds_read_b128 v[70:73], v203 offset:56640
	s_waitcnt lgkmcnt(0)
	v_mfma_f32_16x16x32_bf16 v[70:73], v[70:73], v[8:11], v[74:77]
	s_nop 2
	ds_read_b128 v[74:77], v203 offset:60992
	s_waitcnt lgkmcnt(0)
	v_mfma_f32_16x16x32_bf16 v[74:77], v[74:77], v[8:11], v[78:81]
	s_nop 2
	ds_read_b128 v[78:81], v207 offset:64
	s_waitcnt lgkmcnt(0)
	v_mfma_f32_16x16x32_bf16 v[8:11], v[78:81], v[8:11], v[12:15]
	s_nop 2
	ds_read_b128 v[12:15], v203 offset:128
	s_waitcnt lgkmcnt(0)
	v_mfma_f32_16x16x32_bf16 v[12:15], v[12:15], v[4:7], v[16:19]
	s_nop 2
	ds_read_b128 v[16:19], v203 offset:4480
	s_waitcnt lgkmcnt(0)
	v_mfma_f32_16x16x32_bf16 v[16:19], v[16:19], v[4:7], v[20:23]
	s_nop 2
	ds_read_b128 v[20:23], v203 offset:8832
	s_waitcnt lgkmcnt(0)
	v_mfma_f32_16x16x32_bf16 v[20:23], v[20:23], v[4:7], v[24:27]
	s_nop 2
	ds_read_b128 v[24:27], v204 offset:128
	s_waitcnt lgkmcnt(0)
	v_mfma_f32_16x16x32_bf16 v[24:27], v[24:27], v[4:7], v[28:31]
	s_nop 2
	ds_read_b128 v[28:31], v203 offset:17536
	s_waitcnt lgkmcnt(0)
	v_mfma_f32_16x16x32_bf16 v[28:31], v[28:31], v[4:7], v[32:35]
	s_nop 2
	ds_read_b128 v[32:35], v203 offset:21888
	s_waitcnt lgkmcnt(0)
	v_mfma_f32_16x16x32_bf16 v[32:35], v[32:35], v[4:7], v[36:39]
	s_nop 2
	ds_read_b128 v[36:39], v203 offset:26240
	s_waitcnt lgkmcnt(0)
	v_mfma_f32_16x16x32_bf16 v[36:39], v[36:39], v[4:7], v[40:43]
	s_nop 2
	ds_read_b128 v[40:43], v205 offset:128
	s_waitcnt lgkmcnt(0)
	v_mfma_f32_16x16x32_bf16 v[78:81], v[40:43], v[4:7], v[44:47]
	ds_read_b128 v[40:43], v203 offset:34944
	s_waitcnt lgkmcnt(0)
	v_mfma_f32_16x16x32_bf16 v[82:85], v[40:43], v[4:7], v[48:51]
	ds_read_b128 v[40:43], v203 offset:39296
	s_waitcnt lgkmcnt(0)
	v_mfma_f32_16x16x32_bf16 v[54:57], v[40:43], v[4:7], v[54:57]
	ds_read_b128 v[40:43], v203 offset:43648
	s_waitcnt lgkmcnt(0)
	v_mfma_f32_16x16x32_bf16 v[58:61], v[40:43], v[4:7], v[58:61]
	ds_read_b128 v[40:43], v206 offset:128
	s_waitcnt lgkmcnt(0)
	v_mfma_f32_16x16x32_bf16 v[62:65], v[40:43], v[4:7], v[62:65]
	ds_read_b128 v[40:43], v203 offset:52352
	s_waitcnt lgkmcnt(0)
	v_mfma_f32_16x16x32_bf16 v[66:69], v[40:43], v[4:7], v[66:69]
	ds_read_b128 v[40:43], v203 offset:56704
	s_waitcnt lgkmcnt(0)
	v_mfma_f32_16x16x32_bf16 v[70:73], v[40:43], v[4:7], v[70:73]
	ds_read_b128 v[40:43], v203 offset:61056
	s_waitcnt lgkmcnt(0)
	v_mfma_f32_16x16x32_bf16 v[74:77], v[40:43], v[4:7], v[74:77]
	ds_read_b128 v[40:43], v207 offset:128
	s_waitcnt lgkmcnt(0)
	v_mfma_f32_16x16x32_bf16 v[86:89], v[40:43], v[4:7], v[8:11]
	ds_read_b128 v[4:7], v203 offset:192
	s_waitcnt lgkmcnt(0)
	v_mfma_f32_16x16x32_bf16 v[90:93], v[4:7], v[0:3], v[12:15]
	ds_read_b128 v[4:7], v203 offset:4544
	s_waitcnt lgkmcnt(0)
	v_mfma_f32_16x16x32_bf16 v[162:165], v[4:7], v[0:3], v[16:19]
	ds_read_b128 v[4:7], v203 offset:8896
	s_waitcnt lgkmcnt(0)
	v_mfma_f32_16x16x32_bf16 v[166:169], v[4:7], v[0:3], v[20:23]
	ds_read_b128 v[4:7], v204 offset:192
	s_waitcnt lgkmcnt(0)
	v_mfma_f32_16x16x32_bf16 v[48:51], v[4:7], v[0:3], v[24:27]
	ds_read_b128 v[4:7], v203 offset:17600
	s_waitcnt lgkmcnt(0)
	v_mfma_f32_16x16x32_bf16 v[44:47], v[4:7], v[0:3], v[28:31]
	ds_read_b128 v[4:7], v203 offset:21952
	s_waitcnt lgkmcnt(0)
	v_mfma_f32_16x16x32_bf16 v[40:43], v[4:7], v[0:3], v[32:35]
	ds_read_b128 v[4:7], v203 offset:26304
	s_waitcnt lgkmcnt(0)
	v_mfma_f32_16x16x32_bf16 v[36:39], v[4:7], v[0:3], v[36:39]
	ds_read_b128 v[4:7], v205 offset:192
	s_waitcnt lgkmcnt(0)
	v_mfma_f32_16x16x32_bf16 v[32:35], v[4:7], v[0:3], v[78:81]
	ds_read_b128 v[4:7], v203 offset:35008
	s_waitcnt lgkmcnt(0)
	v_mfma_f32_16x16x32_bf16 v[28:31], v[4:7], v[0:3], v[82:85]
	ds_read_b128 v[4:7], v203 offset:39360
	s_waitcnt lgkmcnt(0)
	v_mfma_f32_16x16x32_bf16 v[24:27], v[4:7], v[0:3], v[54:57]
	ds_read_b128 v[4:7], v203 offset:43712
	s_waitcnt lgkmcnt(0)
	v_mfma_f32_16x16x32_bf16 v[20:23], v[4:7], v[0:3], v[58:61]
	ds_read_b128 v[4:7], v206 offset:192
	s_waitcnt lgkmcnt(0)
	v_mfma_f32_16x16x32_bf16 v[16:19], v[4:7], v[0:3], v[62:65]
	ds_read_b128 v[4:7], v203 offset:52416
	ds_read_b128 v[54:57], v207 offset:192
	s_waitcnt lgkmcnt(1)
	v_mfma_f32_16x16x32_bf16 v[12:15], v[4:7], v[0:3], v[66:69]
	ds_read_b128 v[4:7], v203 offset:56768
	s_waitcnt lgkmcnt(0)
	v_mfma_f32_16x16x32_bf16 v[8:11], v[4:7], v[0:3], v[70:73]
	ds_read_b128 v[4:7], v203 offset:61120
	s_waitcnt lgkmcnt(0)
	v_mfma_f32_16x16x32_bf16 v[4:7], v[4:7], v[0:3], v[74:77]
	v_mfma_f32_16x16x32_bf16 v[0:3], v[54:57], v[0:3], v[86:89]
	v_max_f32_e32 v54, v93, v93
	v_max_f32_e32 v55, v92, v92
	v_max_f32_e32 v54, v55, v54
	v_max_f32_e32 v55, v165, v165
	v_max_f32_e32 v56, v164, v164
	v_max_f32_e32 v55, v56, v55
	v_max3_f32 v54, v90, v91, v54
	v_max3_f32 v55, v162, v163, v55
	s_mov_b32 s0, 0xff800000
	v_max3_f32 v54, v54, s0, v55
	v_max_f32_e32 v55, v169, v169
	v_max_f32_e32 v56, v168, v168
	v_max_f32_e32 v55, v56, v55
	v_max_f32_e32 v56, v51, v51
	v_max_f32_e32 v57, v50, v50
	v_max_f32_e32 v56, v57, v56
	v_max3_f32 v55, v166, v167, v55
	v_max3_f32 v56, v48, v49, v56
	v_max3_f32 v54, v54, v55, v56
	v_max_f32_e32 v55, v47, v47
	v_max_f32_e32 v56, v46, v46
	v_max_f32_e32 v55, v56, v55
	v_max_f32_e32 v56, v43, v43
	v_max_f32_e32 v57, v42, v42
	v_max_f32_e32 v56, v57, v56
	v_max3_f32 v55, v44, v45, v55
	v_max3_f32 v56, v40, v41, v56
	v_max3_f32 v54, v54, v55, v56
	v_max_f32_e32 v55, v39, v39
	v_max_f32_e32 v56, v38, v38
	v_max_f32_e32 v55, v56, v55
	v_max_f32_e32 v56, v35, v35
	v_max_f32_e32 v57, v34, v34
	v_max_f32_e32 v56, v57, v56
	v_max3_f32 v55, v36, v37, v55
	v_max3_f32 v56, v32, v33, v56
	v_max3_f32 v54, v54, v55, v56
	v_max_f32_e32 v55, v31, v31
	v_max_f32_e32 v56, v30, v30
	v_max_f32_e32 v55, v56, v55
	v_max_f32_e32 v56, v27, v27
	v_max_f32_e32 v57, v26, v26
	v_max_f32_e32 v56, v57, v56
	v_max3_f32 v55, v28, v29, v55
	v_max3_f32 v56, v24, v25, v56
	v_max3_f32 v54, v54, v55, v56
	v_max_f32_e32 v55, v23, v23
	v_max_f32_e32 v56, v22, v22
	v_max_f32_e32 v55, v56, v55
	v_max_f32_e32 v56, v19, v19
	v_max_f32_e32 v57, v18, v18
	v_max_f32_e32 v56, v57, v56
	v_max3_f32 v55, v20, v21, v55
	v_max3_f32 v56, v16, v17, v56
	v_max3_f32 v54, v54, v55, v56
	v_max_f32_e32 v55, v15, v15
	v_max_f32_e32 v56, v14, v14
	v_max_f32_e32 v55, v56, v55
	v_max_f32_e32 v56, v11, v11
	v_max_f32_e32 v57, v10, v10
	v_max_f32_e32 v56, v57, v56
	v_max3_f32 v55, v12, v13, v55
	v_max3_f32 v56, v8, v9, v56
	v_max3_f32 v54, v54, v55, v56
	v_max_f32_e32 v55, v7, v7
	v_max_f32_e32 v56, v6, v6
	v_max_f32_e32 v55, v56, v55
	v_max_f32_e32 v56, v3, v3
	v_max_f32_e32 v57, v2, v2
	v_max_f32_e32 v56, v57, v56
	v_max3_f32 v55, v4, v5, v55
	v_max3_f32 v56, v0, v1, v56
	v_max3_f32 v54, v54, v55, v56
	v_and_b32_e32 v56, 64, v188
	v_xor_b32_e32 v55, 16, v188
	v_add_u32_e32 v56, 64, v56
	v_cmp_lt_i32_e32 vcc, v55, v56
	s_barrier
	s_nop 0
	v_cndmask_b32_e32 v55, v188, v55, vcc
	v_lshlrev_b32_e32 v58, 2, v55
	ds_bpermute_b32 v55, v58, v54
	s_waitcnt lgkmcnt(0)
	v_lshlrev_b32_e32 v152, 1, v98
	s_mov_b64 s[22:23], 0
	s_mov_b64 s[24:25], -1
	v_max_f32_e32 v55, v55, v55
	v_max_f32_e32 v54, v54, v55
	v_xor_b32_e32 v55, 32, v188
	v_cmp_lt_i32_e32 vcc, v55, v56
	s_nop 1
	v_cndmask_b32_e32 v55, v188, v55, vcc
	v_lshlrev_b32_e32 v59, 2, v55
	ds_bpermute_b32 v55, v59, v54
	s_waitcnt lgkmcnt(0)
	v_max_f32_e32 v55, v55, v55
	v_max_f32_e32 v60, v54, v55
	v_sub_f32_e32 v54, v90, v60
	v_mul_f32_e32 v54, 0x3fb8aa3b, v54
	v_sub_f32_e32 v55, v91, v60
	v_exp_f32_e32 v54, v54
	v_mul_f32_e32 v55, 0x3fb8aa3b, v55
	v_sub_f32_e32 v56, v92, v60
	v_sub_f32_e32 v57, v93, v60
	v_exp_f32_e32 v55, v55
	v_mul_f32_e32 v56, 0x3fb8aa3b, v56
	v_mul_f32_e32 v57, 0x3fb8aa3b, v57
	v_exp_f32_e32 v56, v56
	v_exp_f32_e32 v57, v57
	v_add_f32_e32 v61, 0, v54
	v_add_f32_e32 v61, v55, v61
	v_add_f32_e32 v61, v56, v61
	v_cvt_pk_bf16_f32 v54, v54, v55
	v_cvt_pk_bf16_f32 v55, v56, v57
	v_sub_f32_e32 v56, v162, v60
	v_add_f32_e32 v61, v57, v61
	v_mul_f32_e32 v56, 0x3fb8aa3b, v56
	v_sub_f32_e32 v57, v163, v60
	v_sub_f32_e32 v62, v164, v60
	v_sub_f32_e32 v63, v165, v60
	v_exp_f32_e32 v56, v56
	v_mul_f32_e32 v57, 0x3fb8aa3b, v57
	v_mul_f32_e32 v62, 0x3fb8aa3b, v62
	v_mul_f32_e32 v63, 0x3fb8aa3b, v63
	v_exp_f32_e32 v57, v57
	v_exp_f32_e32 v62, v62
	v_exp_f32_e32 v63, v63
	v_add_f32_e32 v61, v56, v61
	v_add_f32_e32 v61, v57, v61
	v_cvt_pk_bf16_f32 v56, v56, v57
	v_cvt_pk_bf16_f32 v57, v62, v63
	ds_write2_b64 v215, v[54:55], v[56:57] offset1:4
	v_sub_f32_e32 v54, v166, v60
	v_mul_f32_e32 v54, 0x3fb8aa3b, v54
	v_sub_f32_e32 v55, v167, v60
	v_exp_f32_e32 v54, v54
	v_mul_f32_e32 v55, 0x3fb8aa3b, v55
	v_sub_f32_e32 v56, v168, v60
	v_exp_f32_e32 v55, v55
	v_mul_f32_e32 v56, 0x3fb8aa3b, v56
	v_sub_f32_e32 v57, v169, v60
	v_add_f32_e32 v61, v62, v61
	v_exp_f32_e32 v56, v56
	v_mul_f32_e32 v57, 0x3fb8aa3b, v57
	v_sub_f32_e32 v48, v48, v60
	v_add_f32_e32 v61, v63, v61
	v_exp_f32_e32 v57, v57
	v_mul_f32_e32 v48, 0x3fb8aa3b, v48
	v_sub_f32_e32 v49, v49, v60
	v_add_f32_e32 v61, v54, v61
	v_exp_f32_e32 v48, v48
	v_mul_f32_e32 v49, 0x3fb8aa3b, v49
	v_sub_f32_e32 v50, v50, v60
	v_add_f32_e32 v61, v55, v61
	v_exp_f32_e32 v49, v49
	v_mul_f32_e32 v50, 0x3fb8aa3b, v50
	v_sub_f32_e32 v51, v51, v60
	v_add_f32_e32 v61, v56, v61
	v_exp_f32_e32 v50, v50
	v_mul_f32_e32 v51, 0x3fb8aa3b, v51
	v_sub_f32_e32 v44, v44, v60
	v_add_f32_e32 v61, v57, v61
	v_exp_f32_e32 v51, v51
	v_mul_f32_e32 v44, 0x3fb8aa3b, v44
	v_sub_f32_e32 v45, v45, v60
	v_cvt_pk_bf16_f32 v54, v54, v55
	v_cvt_pk_bf16_f32 v55, v56, v57
	v_add_f32_e32 v56, v48, v61
	v_exp_f32_e32 v44, v44
	v_mul_f32_e32 v45, 0x3fb8aa3b, v45
	v_sub_f32_e32 v46, v46, v60
	v_add_f32_e32 v56, v49, v56
	v_exp_f32_e32 v45, v45
	v_mul_f32_e32 v46, 0x3fb8aa3b, v46
	v_sub_f32_e32 v47, v47, v60
	v_add_f32_e32 v56, v50, v56
	v_exp_f32_e32 v46, v46
	v_mul_f32_e32 v47, 0x3fb8aa3b, v47
	v_sub_f32_e32 v40, v40, v60
	v_add_f32_e32 v56, v51, v56
	v_cvt_pk_bf16_f32 v48, v48, v49
	v_cvt_pk_bf16_f32 v49, v50, v51
	v_exp_f32_e32 v47, v47
	v_mul_f32_e32 v40, 0x3fb8aa3b, v40
	v_sub_f32_e32 v41, v41, v60
	ds_write2_b64 v215, v[54:55], v[48:49] offset0:8 offset1:12
	v_add_f32_e32 v48, v44, v56
	v_exp_f32_e32 v40, v40
	v_mul_f32_e32 v41, 0x3fb8aa3b, v41
	v_sub_f32_e32 v42, v42, v60
	v_add_f32_e32 v48, v45, v48
	v_exp_f32_e32 v41, v41
	v_mul_f32_e32 v42, 0x3fb8aa3b, v42
	v_sub_f32_e32 v43, v43, v60
	v_add_f32_e32 v48, v46, v48
	v_exp_f32_e32 v42, v42
	v_mul_f32_e32 v43, 0x3fb8aa3b, v43
	v_sub_f32_e32 v36, v36, v60
	v_add_f32_e32 v48, v47, v48
	v_exp_f32_e32 v43, v43
	v_mul_f32_e32 v36, 0x3fb8aa3b, v36
	v_sub_f32_e32 v37, v37, v60
	v_cvt_pk_bf16_f32 v44, v44, v45
	v_cvt_pk_bf16_f32 v45, v46, v47
	v_add_f32_e32 v46, v40, v48
	v_exp_f32_e32 v36, v36
	v_mul_f32_e32 v37, 0x3fb8aa3b, v37
	v_sub_f32_e32 v38, v38, v60
	v_add_f32_e32 v46, v41, v46
	v_exp_f32_e32 v37, v37
	v_mul_f32_e32 v38, 0x3fb8aa3b, v38
	v_sub_f32_e32 v39, v39, v60
	v_add_f32_e32 v46, v42, v46
	v_exp_f32_e32 v38, v38
	v_mul_f32_e32 v39, 0x3fb8aa3b, v39
	v_sub_f32_e32 v32, v32, v60
	v_add_f32_e32 v46, v43, v46
	v_cvt_pk_bf16_f32 v40, v40, v41
	v_cvt_pk_bf16_f32 v41, v42, v43
	v_exp_f32_e32 v39, v39
	v_mul_f32_e32 v32, 0x3fb8aa3b, v32
	v_sub_f32_e32 v33, v33, v60
	ds_write2_b64 v215, v[44:45], v[40:41] offset0:16 offset1:20
	v_add_f32_e32 v40, v36, v46
	v_exp_f32_e32 v32, v32
	v_mul_f32_e32 v33, 0x3fb8aa3b, v33
	v_sub_f32_e32 v34, v34, v60
	v_add_f32_e32 v40, v37, v40
	v_exp_f32_e32 v33, v33
	v_mul_f32_e32 v34, 0x3fb8aa3b, v34
	v_sub_f32_e32 v35, v35, v60
	v_add_f32_e32 v40, v38, v40
	v_exp_f32_e32 v34, v34
	v_mul_f32_e32 v35, 0x3fb8aa3b, v35
	v_sub_f32_e32 v28, v28, v60
	v_add_f32_e32 v40, v39, v40
	v_exp_f32_e32 v35, v35
	v_mul_f32_e32 v28, 0x3fb8aa3b, v28
	v_sub_f32_e32 v29, v29, v60
	v_cvt_pk_bf16_f32 v36, v36, v37
	v_cvt_pk_bf16_f32 v37, v38, v39
	v_add_f32_e32 v38, v32, v40
	v_exp_f32_e32 v28, v28
	v_mul_f32_e32 v29, 0x3fb8aa3b, v29
	v_sub_f32_e32 v30, v30, v60
	v_add_f32_e32 v38, v33, v38
	v_exp_f32_e32 v29, v29
	v_mul_f32_e32 v30, 0x3fb8aa3b, v30
	v_sub_f32_e32 v31, v31, v60
	v_add_f32_e32 v38, v34, v38
	v_exp_f32_e32 v30, v30
	v_mul_f32_e32 v31, 0x3fb8aa3b, v31
	v_sub_f32_e32 v24, v24, v60
	v_add_f32_e32 v38, v35, v38
	v_cvt_pk_bf16_f32 v32, v32, v33
	v_cvt_pk_bf16_f32 v33, v34, v35
	v_exp_f32_e32 v31, v31
	v_mul_f32_e32 v24, 0x3fb8aa3b, v24
	v_sub_f32_e32 v25, v25, v60
	ds_write2_b64 v215, v[36:37], v[32:33] offset0:24 offset1:28
	v_add_f32_e32 v32, v28, v38
	v_exp_f32_e32 v24, v24
	v_mul_f32_e32 v25, 0x3fb8aa3b, v25
	v_sub_f32_e32 v26, v26, v60
	v_add_f32_e32 v32, v29, v32
	v_exp_f32_e32 v25, v25
	v_mul_f32_e32 v26, 0x3fb8aa3b, v26
	v_sub_f32_e32 v27, v27, v60
	v_add_f32_e32 v32, v30, v32
	v_exp_f32_e32 v26, v26
	v_mul_f32_e32 v27, 0x3fb8aa3b, v27
	v_sub_f32_e32 v20, v20, v60
	v_add_f32_e32 v32, v31, v32
	v_exp_f32_e32 v27, v27
	v_mul_f32_e32 v20, 0x3fb8aa3b, v20
	v_sub_f32_e32 v21, v21, v60
	v_cvt_pk_bf16_f32 v28, v28, v29
	v_cvt_pk_bf16_f32 v29, v30, v31
	v_add_f32_e32 v30, v24, v32
	v_exp_f32_e32 v20, v20
	v_mul_f32_e32 v21, 0x3fb8aa3b, v21
	v_sub_f32_e32 v22, v22, v60
	v_add_f32_e32 v30, v25, v30
	v_exp_f32_e32 v21, v21
	v_mul_f32_e32 v22, 0x3fb8aa3b, v22
	v_sub_f32_e32 v23, v23, v60
	v_add_f32_e32 v30, v26, v30
	v_exp_f32_e32 v22, v22
	v_mul_f32_e32 v23, 0x3fb8aa3b, v23
	v_sub_f32_e32 v16, v16, v60
	v_add_f32_e32 v30, v27, v30
	v_cvt_pk_bf16_f32 v24, v24, v25
	v_cvt_pk_bf16_f32 v25, v26, v27
	v_exp_f32_e32 v23, v23
	v_mul_f32_e32 v16, 0x3fb8aa3b, v16
	v_sub_f32_e32 v17, v17, v60
	ds_write2_b64 v215, v[28:29], v[24:25] offset0:32 offset1:36
	v_add_f32_e32 v24, v20, v30
	v_exp_f32_e32 v16, v16
	v_mul_f32_e32 v17, 0x3fb8aa3b, v17
	v_sub_f32_e32 v18, v18, v60
	v_add_f32_e32 v24, v21, v24
	v_exp_f32_e32 v17, v17
	v_mul_f32_e32 v18, 0x3fb8aa3b, v18
	v_sub_f32_e32 v19, v19, v60
	v_add_f32_e32 v24, v22, v24
	v_exp_f32_e32 v18, v18
	v_mul_f32_e32 v19, 0x3fb8aa3b, v19
	v_sub_f32_e32 v12, v12, v60
	v_add_f32_e32 v24, v23, v24
	v_exp_f32_e32 v19, v19
	v_mul_f32_e32 v12, 0x3fb8aa3b, v12
	v_sub_f32_e32 v13, v13, v60
	v_cvt_pk_bf16_f32 v20, v20, v21
	v_cvt_pk_bf16_f32 v21, v22, v23
	v_add_f32_e32 v22, v16, v24
	v_exp_f32_e32 v12, v12
	v_mul_f32_e32 v13, 0x3fb8aa3b, v13
	v_sub_f32_e32 v14, v14, v60
	v_add_f32_e32 v22, v17, v22
	v_exp_f32_e32 v13, v13
	v_mul_f32_e32 v14, 0x3fb8aa3b, v14
	v_sub_f32_e32 v15, v15, v60
	v_add_f32_e32 v22, v18, v22
	v_exp_f32_e32 v14, v14
	v_mul_f32_e32 v15, 0x3fb8aa3b, v15
	v_sub_f32_e32 v8, v8, v60
	v_add_f32_e32 v22, v19, v22
	v_cvt_pk_bf16_f32 v16, v16, v17
	v_cvt_pk_bf16_f32 v17, v18, v19
	v_exp_f32_e32 v15, v15
	v_mul_f32_e32 v8, 0x3fb8aa3b, v8
	v_sub_f32_e32 v9, v9, v60
	ds_write2_b64 v215, v[20:21], v[16:17] offset0:40 offset1:44
	v_add_f32_e32 v16, v12, v22
	v_exp_f32_e32 v8, v8
	v_mul_f32_e32 v9, 0x3fb8aa3b, v9
	v_sub_f32_e32 v10, v10, v60
	v_add_f32_e32 v16, v13, v16
	v_exp_f32_e32 v9, v9
	v_mul_f32_e32 v10, 0x3fb8aa3b, v10
	v_sub_f32_e32 v11, v11, v60
	v_add_f32_e32 v16, v14, v16
	v_exp_f32_e32 v10, v10
	v_mul_f32_e32 v11, 0x3fb8aa3b, v11
	v_sub_f32_e32 v4, v4, v60
	v_add_f32_e32 v16, v15, v16
	v_exp_f32_e32 v11, v11
	v_mul_f32_e32 v4, 0x3fb8aa3b, v4
	v_sub_f32_e32 v5, v5, v60
	v_sub_f32_e32 v0, v0, v60
	v_cvt_pk_bf16_f32 v12, v12, v13
	v_add_f32_e32 v13, v8, v16
	v_exp_f32_e32 v4, v4
	v_mul_f32_e32 v5, 0x3fb8aa3b, v5
	v_sub_f32_e32 v6, v6, v60
	v_mul_f32_e32 v0, 0x3fb8aa3b, v0
	v_add_f32_e32 v13, v9, v13
	v_exp_f32_e32 v5, v5
	v_mul_f32_e32 v6, 0x3fb8aa3b, v6
	v_sub_f32_e32 v7, v7, v60
	v_exp_f32_e32 v16, v0
	v_sub_f32_e32 v0, v1, v60
	v_add_f32_e32 v13, v10, v13
	v_exp_f32_e32 v6, v6
	v_mul_f32_e32 v7, 0x3fb8aa3b, v7
	v_mul_f32_e32 v0, 0x3fb8aa3b, v0
	v_add_f32_e32 v13, v11, v13
	v_exp_f32_e32 v7, v7
	v_exp_f32_e32 v17, v0
	v_sub_f32_e32 v0, v2, v60
	v_add_f32_e32 v13, v4, v13
	v_mul_f32_e32 v0, 0x3fb8aa3b, v0
	v_add_f32_e32 v13, v5, v13
	v_exp_f32_e32 v18, v0
	v_sub_f32_e32 v0, v3, v60
	v_add_f32_e32 v13, v6, v13
	v_mul_f32_e32 v0, 0x3fb8aa3b, v0
	v_add_f32_e32 v13, v7, v13
	v_exp_f32_e32 v3, v0
	v_add_f32_e32 v0, v16, v13
	v_add_f32_e32 v0, v17, v0
	v_add_f32_e32 v0, v18, v0
	v_add_f32_e32 v2, v3, v0
	ds_bpermute_b32 v19, v58, v2
	v_cvt_pk_bf16_f32 v13, v14, v15
	v_cvt_pk_bf16_f32 v0, v8, v9
	v_cvt_pk_bf16_f32 v1, v10, v11
	ds_write2_b64 v215, v[12:13], v[0:1] offset0:48 offset1:52
	s_waitcnt lgkmcnt(1)
	v_add_f32_e32 v2, v2, v19
	ds_bpermute_b32 v8, v59, v2
	v_sub_f32_e32 v0, 0xff800000, v60
	v_mul_f32_e32 v0, 0x3fb8aa3b, v0
	v_exp_f32_e32 v9, v0
	v_cvt_pk_bf16_f32 v0, v4, v5
	s_waitcnt lgkmcnt(0)
	v_add_f32_e32 v2, v2, v8
	v_cvt_pk_bf16_f32 v1, v6, v7
	v_add_f32_e32 v4, v9, v2
	v_div_scale_f32 v5, s[20:21], v4, v4, 1.0
	v_rcp_f32_e32 v6, v5
	v_cvt_pk_bf16_f32 v2, v16, v17
	v_cvt_pk_bf16_f32 v3, v18, v3
	ds_write2_b64 v215, v[0:1], v[2:3] offset0:56 offset1:60
	v_fma_f32 v0, -v5, v6, 1.0
	v_fmac_f32_e32 v6, v0, v6
	v_div_scale_f32 v0, vcc, 1.0, v4, 1.0
	v_mul_f32_e32 v1, v0, v6
	v_fma_f32 v2, -v5, v1, v0
	v_fmac_f32_e32 v1, v2, v6
	v_fma_f32 v0, -v5, v1, v0
	v_div_fmas_f32 v0, v0, v6, v1
	v_div_fixup_f32 v32, v0, v4, 1.0
	v_lshl_add_u64 v[0:1], v[52:53], 0, v[152:153]
	s_mov_b64 s[20:21], 0x17100000
	v_lshl_add_u64 v[34:35], v[0:1], 0, s[20:21]
	v_mov_b32_e32 v33, v32
.LBB0_182:
	s_xor_b64 s[20:21], s[24:25], -1
	s_lshl_b64 s[24:25], s[22:23], 1
	s_add_u32 s24, s6, s24
	s_addc_u32 s25, s7, s25
	v_lshl_add_u64 v[0:1], s[24:25], 0, v[132:133]
	v_lshl_add_u64 v[0:1], v[0:1], 0, v[148:149]
	v_lshl_add_u64 v[4:5], s[24:25], 0, v[134:135]
	flat_load_dwordx4 v[0:3], v[0:1] offset:2048
	v_lshl_add_u64 v[4:5], v[4:5], 0, v[148:149]
	flat_load_dwordx4 v[4:7], v[4:5] offset:2048
	v_lshl_add_u64 v[248:249], s[24:25], 0, v[136:137]
	v_lshl_add_u64 v[248:249], v[248:249], 0, v[150:151]
	global_load_dwordx4 v[224:227], v[248:249], off offset:2048
	v_lshl_add_u64 v[250:251], s[24:25], 0, v[138:139]
	v_lshl_add_u64 v[250:251], v[250:251], 0, v[150:151]
	global_load_dwordx4 v[228:231], v[250:251], off offset:2048
	v_lshl_add_u64 v[248:249], s[24:25], 0, v[140:141]
	v_lshl_add_u64 v[248:249], v[248:249], 0, v[158:159]
	global_load_dwordx4 v[232:235], v[248:249], off offset:2048
	v_lshl_add_u64 v[250:251], s[24:25], 0, v[142:143]
	v_lshl_add_u64 v[250:251], v[250:251], 0, v[158:159]
	global_load_dwordx4 v[236:239], v[250:251], off offset:2048
	v_lshl_add_u64 v[248:249], s[24:25], 0, v[144:145]
	v_lshl_add_u64 v[248:249], v[248:249], 0, v[160:161]
	global_load_dwordx4 v[240:243], v[248:249], off offset:2048
	v_lshl_add_u64 v[250:251], s[24:25], 0, v[146:147]
	v_lshl_add_u64 v[250:251], v[250:251], 0, v[160:161]
	global_load_dwordx4 v[244:247], v[250:251], off offset:2048
	v_mov_b32_e32 v28, 0
	s_mov_b32 s0, 0
	v_mov_b32_e32 v29, v28
	v_mov_b32_e32 v30, v28
	v_mov_b32_e32 v31, v28
	v_mov_b32_e32 v16, v28
	v_mov_b32_e32 v17, v28
	v_mov_b32_e32 v18, v28
	v_mov_b32_e32 v19, v28
	v_mov_b32_e32 v9, v28
	v_mov_b32_e32 v10, v28
	v_mov_b32_e32 v11, v28
	v_mov_b32_e32 v12, v28
	v_mov_b32_e32 v13, v28
	v_mov_b32_e32 v14, v28
	v_mov_b32_e32 v15, v28
	v_mov_b32_e32 v20, v28
	v_mov_b32_e32 v21, v28
	v_mov_b32_e32 v22, v28
	v_mov_b32_e32 v23, v28
	v_mov_b32_e32 v24, v28
	v_mov_b32_e32 v25, v28
	v_mov_b32_e32 v26, v28
	v_mov_b32_e32 v27, v28
	s_waitcnt vmcnt(0) lgkmcnt(0)
	v_and_b32_e32 v8, 0xffff, v0
	v_lshrrev_b32_e32 v0, 16, v0
	v_lshl_or_b32 v8, v4, 16, v8
	v_and_or_b32 v0, v4, s59, v0
	ds_write2_b32 v208, v8, v0 offset1:132
	v_and_b32_e32 v0, 0xffff, v1
	v_lshrrev_b32_e32 v1, 16, v1
	v_lshl_or_b32 v0, v5, 16, v0
	v_and_or_b32 v1, v5, s59, v1
	v_add_u32_e32 v4, 0x400, v208
	ds_write2_b32 v4, v0, v1 offset0:8 offset1:140
	v_and_b32_e32 v0, 0xffff, v2
	v_lshrrev_b32_e32 v1, 16, v2
	v_lshl_or_b32 v0, v6, 16, v0
	v_and_or_b32 v1, v6, s59, v1
	v_add_u32_e32 v2, 0x800, v208
	ds_write2_b32 v2, v0, v1 offset0:16 offset1:148
	v_and_b32_e32 v0, 0xffff, v3
	v_lshrrev_b32_e32 v1, 16, v3
	v_lshl_or_b32 v0, v7, 16, v0
	v_and_or_b32 v1, v7, s59, v1
	v_add_u32_e32 v2, 0xc00, v208
	ds_write2_b32 v2, v0, v1 offset0:24 offset1:156
	v_mov_b32_e32 v0, v224
	v_mov_b32_e32 v1, v225
	v_mov_b32_e32 v2, v226
	v_mov_b32_e32 v3, v227
	v_mov_b32_e32 v4, v228
	v_mov_b32_e32 v5, v229
	v_mov_b32_e32 v6, v230
	v_mov_b32_e32 v7, v231
	v_and_b32_e32 v8, 0xffff, v0
	v_lshrrev_b32_e32 v0, 16, v0
	v_lshl_or_b32 v8, v4, 16, v8
	v_and_or_b32 v0, v4, s59, v0
	ds_write2_b32 v209, v8, v0 offset1:132
	v_and_b32_e32 v0, 0xffff, v1
	v_lshrrev_b32_e32 v1, 16, v1
	v_lshl_or_b32 v0, v5, 16, v0
	v_and_or_b32 v1, v5, s59, v1
	v_add_u32_e32 v4, 0x400, v209
	ds_write2_b32 v4, v0, v1 offset0:8 offset1:140
	v_and_b32_e32 v0, 0xffff, v2
	v_lshrrev_b32_e32 v1, 16, v2
	v_lshl_or_b32 v0, v6, 16, v0
	v_and_or_b32 v1, v6, s59, v1
	v_add_u32_e32 v2, 0x800, v209
	ds_write2_b32 v2, v0, v1 offset0:16 offset1:148
	v_and_b32_e32 v0, 0xffff, v3
	v_lshrrev_b32_e32 v1, 16, v3
	v_lshl_or_b32 v0, v7, 16, v0
	v_and_or_b32 v1, v7, s59, v1
	v_add_u32_e32 v2, 0xc00, v209
	ds_write2_b32 v2, v0, v1 offset0:24 offset1:156
	v_mov_b32_e32 v0, v232
	v_mov_b32_e32 v1, v233
	v_mov_b32_e32 v2, v234
	v_mov_b32_e32 v3, v235
	v_mov_b32_e32 v4, v236
	v_mov_b32_e32 v5, v237
	v_mov_b32_e32 v6, v238
	v_mov_b32_e32 v7, v239
	v_and_b32_e32 v8, 0xffff, v0
	v_lshrrev_b32_e32 v0, 16, v0
	v_lshl_or_b32 v8, v4, 16, v8
	v_and_or_b32 v0, v4, s59, v0
	ds_write2_b32 v210, v8, v0 offset1:132
	v_and_b32_e32 v0, 0xffff, v1
	v_lshrrev_b32_e32 v1, 16, v1
	v_lshl_or_b32 v0, v5, 16, v0
	v_and_or_b32 v1, v5, s59, v1
	v_add_u32_e32 v4, 0x400, v210
	ds_write2_b32 v4, v0, v1 offset0:8 offset1:140
	v_and_b32_e32 v0, 0xffff, v2
	v_lshrrev_b32_e32 v1, 16, v2
	v_lshl_or_b32 v0, v6, 16, v0
	v_and_or_b32 v1, v6, s59, v1
	v_add_u32_e32 v2, 0x800, v210
	ds_write2_b32 v2, v0, v1 offset0:16 offset1:148
	v_and_b32_e32 v0, 0xffff, v3
	v_lshrrev_b32_e32 v1, 16, v3
	v_lshl_or_b32 v0, v7, 16, v0
	v_and_or_b32 v1, v7, s59, v1
	v_add_u32_e32 v2, 0xc00, v210
	ds_write2_b32 v2, v0, v1 offset0:24 offset1:156
	v_mov_b32_e32 v0, v240
	v_mov_b32_e32 v1, v241
	v_mov_b32_e32 v2, v242
	v_mov_b32_e32 v3, v243
	v_mov_b32_e32 v4, v244
	v_mov_b32_e32 v5, v245
	v_mov_b32_e32 v6, v246
	v_mov_b32_e32 v7, v247
	v_and_b32_e32 v8, 0xffff, v0
	v_lshrrev_b32_e32 v0, 16, v0
	v_lshl_or_b32 v8, v4, 16, v8
	v_and_or_b32 v0, v4, s59, v0
	ds_write2_b32 v211, v8, v0 offset1:132
	v_and_b32_e32 v0, 0xffff, v1
	v_lshrrev_b32_e32 v1, 16, v1
	v_lshl_or_b32 v0, v5, 16, v0
	v_and_or_b32 v1, v5, s59, v1
	v_add_u32_e32 v4, 0x400, v211
	ds_write2_b32 v4, v0, v1 offset0:8 offset1:140
	v_and_b32_e32 v0, 0xffff, v2
	v_lshrrev_b32_e32 v1, 16, v2
	v_lshl_or_b32 v0, v6, 16, v0
	v_and_or_b32 v1, v6, s59, v1
	v_add_u32_e32 v2, 0x800, v211
	ds_write2_b32 v2, v0, v1 offset0:16 offset1:148
	v_and_b32_e32 v0, 0xffff, v3
	v_lshrrev_b32_e32 v1, 16, v3
	v_lshl_or_b32 v0, v7, 16, v0
	v_and_or_b32 v1, v7, s59, v1
	v_add_u32_e32 v2, 0xc00, v211
	ds_write2_b32 v2, v0, v1 offset0:24 offset1:156
	v_mov_b32_e32 v0, v28
	v_mov_b32_e32 v1, v28
	v_mov_b32_e32 v2, v28
	v_mov_b32_e32 v3, v28
	v_mov_b32_e32 v4, v28
	v_mov_b32_e32 v5, v28
	v_mov_b32_e32 v6, v28
	v_mov_b32_e32 v7, v28
	v_mov_b32_e32 v8, v28
	s_waitcnt lgkmcnt(0)
	s_barrier
